# v026_prefetch
# speedup vs baseline: 1.0012x; 1.0012x over previous
; __device__ __forceinline__ void phase_mixers(const Params& p, int cidx, int layer) {
;   __shared__ int s_item;
;   int* ctr = (int*)(p.ws + WS_CTR) + cidx;
;   constexpr int N_SSM = 128 * (1 + (MIXDBL & 1)), N_POOL = 256 * (1 + ((MIXDBL >> 2) & 1)), N_ATT = 512 * (1 + ((MIXDBL >> 1) & 1));
;   const int n_cv = (layer == 0) ? CV_B * (1 + ((MIXDBL >> 3) & 1)) : 0;
; #pragma unroll 1
;   for (;;) {
;     const int tidx = opaque_tid();
;     const int wid = tidx >> 6;
;     __syncthreads();
;     if (tidx == 0) s_item = atomicAdd(ctr, 1);
;     __syncthreads();
;     const int it = s_item;
;     if (it >= N_SSM + N_POOL + N_ATT + n_cv) break;
.LBB0_68:
	s_and_b64 vcc, exec, s[8:9]
	s_cbranch_vccz .LBB0_216
	s_cmp_gt_i32 s57, 0
	s_mov_b64 s[8:9], -1
	s_cbranch_scc0 .LBB0_218
	s_lshl_b32 s6, s64, 1
	s_ashr_i32 s7, s6, 31
	s_lshl_b64 s[6:7], s[6:7], 2
	s_add_u32 s6, s86, s6
	s_addc_u32 s7, s87, s7
	s_mov_b32 s98, 0
	s_add_u32 s28, s6, 0x43d10000
	s_addc_u32 s29, s7, 0
	s_add_i32 s6, s44, 4
	s_cmp_lt_u32 s6, 11
	s_movk_i32 s6, 0x624
	v_writelane_b32 v255, s57, 3
	s_cselect_b32 s11, s6, 0x380
	s_mov_b32 s10, s64
	s_ashr_i32 s65, s64, 31
	s_lshl_b32 s8, s64, 10
	v_writelane_b32 v255, s10, 4
	s_lshl_b64 s[6:7], s[64:65], 19
	s_ashr_i32 s9, s8, 31
	v_writelane_b32 v255, s11, 5
	s_lshl_b32 s10, s64, 6
	s_add_u32 s12, s86, 0x10880000
	v_writelane_b32 v255, s12, 6
	s_addc_u32 s12, s87, 0
	v_writelane_b32 v255, s12, 7
	v_readlane_b32 s12, v254, 33
	v_readlane_b32 s18, v254, 39
	v_readlane_b32 s19, v254, 40
	s_add_u32 s12, s18, 0x100000
	v_writelane_b32 v255, s12, 8
	s_addc_u32 s12, s19, 0
	v_readlane_b32 s13, v254, 34
	v_writelane_b32 v255, s12, 9
	s_add_u32 s12, s86, 0x10400000
	v_readlane_b32 s64, v254, 49
	s_addc_u32 s13, s87, 0
	v_readlane_b32 s69, v254, 54
	v_readlane_b32 s74, v254, 59
	v_writelane_b32 v255, s12, 10
	v_readlane_b32 s68, v254, 53
	v_readlane_b32 s75, v254, 60
	s_add_u32 s69, s74, 0x800000
	v_writelane_b32 v255, s13, 11
	s_mov_b32 s68, s10
	s_addc_u32 s10, s75, 0
	v_readlane_b32 s65, v254, 50
	v_readlane_b32 s79, v255, 0
	v_writelane_b32 v255, s10, 12
	s_add_u32 s10, s86, 0xe000000
	s_mov_b32 s65, s11
	s_addc_u32 s11, s87, 0
	v_writelane_b32 v255, s10, 13
	v_readlane_b32 s16, v254, 37
	v_readlane_b32 s17, v254, 38
	v_writelane_b32 v255, s11, 14
	s_add_u32 s10, s80, 0x4000000
	v_writelane_b32 v255, s10, 15
	s_addc_u32 s10, s81, 0
	v_writelane_b32 v255, s10, 16
	s_add_u32 s10, s86, 0x6000000
	s_addc_u32 s11, s87, 0
	v_writelane_b32 v255, s10, 17
	v_readlane_b32 s70, v254, 55
	v_readlane_b32 s71, v254, 56
	v_writelane_b32 v255, s11, 18
	s_add_u32 s10, s16, 0xc000000
	v_writelane_b32 v255, s10, 19
	s_addc_u32 s10, s17, 0
	v_writelane_b32 v255, s10, 20
	s_add_u32 s10, s86, 0x10000000
	s_addc_u32 s11, s87, 0
	v_writelane_b32 v255, s10, 21
	v_readlane_b32 s20, v254, 41
	v_readlane_b32 s78, v254, 63
	v_writelane_b32 v255, s11, 22
	s_add_u32 s10, s86, 0xc000000
	s_addc_u32 s11, s87, 0
	s_add_u32 s70, s86, 0x43d14100
	s_addc_u32 s71, s87, 0
	s_add_u32 s74, s86, 0x14900000
	s_addc_u32 s75, s87, 0
	s_lshl_b64 s[8:9], s[8:9], 2
	v_readlane_b32 s21, v254, 42
	s_add_u32 s78, s20, s8
	s_addc_u32 s79, s21, s9
	v_writelane_b32 v255, s10, 23
	s_add_u32 s12, s86, 0x22900000
	s_addc_u32 s13, s87, 0
	v_writelane_b32 v255, s11, 24
	v_writelane_b32 v255, s12, 25
	v_readlane_b32 s72, v254, 57
	v_readlane_b32 s73, v254, 58
	v_writelane_b32 v255, s13, 26
	s_add_u32 s12, s86, 0x3f900000
	v_writelane_b32 v255, s12, 27
	s_addc_u32 s12, s87, 0
	v_writelane_b32 v255, s12, 28
	s_add_u32 s12, s86, 0x41d00000
	v_writelane_b32 v255, s12, 29
	s_addc_u32 s12, s87, 0
	v_writelane_b32 v255, s12, 30
	s_add_u32 s12, s86, 0x2e900000
	v_writelane_b32 v255, s12, 31
	s_addc_u32 s12, s87, 0
	v_writelane_b32 v255, s12, 32
	s_add_u32 s12, s86, 0x43d00000
	v_writelane_b32 v255, s12, 33
	s_addc_u32 s12, s87, 0
	v_writelane_b32 v255, s12, 34
	s_add_u32 s8, s72, s8
	v_writelane_b32 v255, s8, 35
	s_addc_u32 s8, s73, s9
	s_add_u32 s6, s86, s6
	s_addc_u32 s7, s87, s7
	v_writelane_b32 v255, s8, 36
	s_add_u32 s8, s6, 0x10860000
	s_addc_u32 s9, s7, 0
	v_writelane_b32 v255, s8, 37
	v_readlane_b32 s76, v254, 61
	v_readlane_b32 s66, v254, 51
	v_writelane_b32 v255, s9, 38
	v_writelane_b32 v255, s44, 39
	v_readlane_b32 s67, v254, 52
	v_readlane_b32 s77, v254, 62
	v_writelane_b32 v255, s45, 40
	s_add_u32 s76, s86, 0x3fd03c00
	v_writelane_b32 v255, s46, 41
	s_mov_b64 s[66:67], s[28:29]
	s_mov_b64 s[72:73], s[6:7]
	s_addc_u32 s77, s87, 0
	v_writelane_b32 v255, s47, 42
	v_readlane_b32 s14, v254, 35
	v_readlane_b32 s15, v254, 36
	v_readlane_b32 s22, v254, 43
	v_readlane_b32 s23, v254, 44
	v_readlane_b32 s24, v254, 45
	v_readlane_b32 s25, v254, 46
	v_readlane_b32 s26, v254, 47
	v_readlane_b32 s27, v254, 48
	s_branch .LBB0_73

; __device__ __forceinline__ void phase_mixers(const Params& p, int cidx, int layer) {
;     ...
;   for (;;) {
;     const int tidx = opaque_tid();
;     const int wid = tidx >> 6;
;     __syncthreads();
;     if (tidx == 0) s_item = atomicAdd(ctr, 1);
;     __syncthreads();
;     const int it = s_item;
;     if (it >= N_SSM + N_POOL + N_ATT + n_cv) break;
;     if (it < N_SSM) ssm_item(p, layer, it & 127, tidx);
;     else if (it < N_SSM + N_POOL) pool_block_item(p, layer, (it - N_SSM) & 255, tidx);
;     else if (it < N_SSM + N_POOL + N_ATT) attn_wave_item(p, ((it - N_SSM - N_POOL) & 511) * 8 + wid, tidx);
;     else cv_item_B(p, (it - N_SSM - N_POOL - N_ATT) % CV_B, tidx);
.LBB0_73:
	v_mov_b32_e32 v164, v210
	s_nop 0
	v_cmp_eq_u32_e32 vcc, 0, v164
	s_barrier
	s_and_saveexec_b64 s[6:7], vcc
	s_cbranch_execz .LBB0_77
	s_cmp_lg_u32 s98, 0
	s_cbranch_scc1 .Lqm_have
	v_mov_b32_e32 v1, 1
	global_atomic_add v252, v163, v1, s[66:67] sc0
.Lqm_have:
	s_waitcnt vmcnt(0)
	v_mov_b32_e32 v0, v252
	ds_write_b32 v163, v0 offset:20
	v_readfirstlane_b32 s8, v0
	s_mov_b32 s98, 0
	s_nop 1
	s_sub_u32 s8, s8, 0x80
	s_cmp_lt_u32 s8, 0x300
	s_cbranch_scc0 .Lqm_done
	v_mov_b32_e32 v1, 1
	global_atomic_add v252, v163, v1, s[66:67] sc0
	s_mov_b32 s98, 1
.Lqm_done:
.LBB0_77:
	s_or_b64 exec, exec, s[6:7]
	s_waitcnt lgkmcnt(0)
	s_barrier
	ds_read_b32 v0, v163 offset:20
	s_mov_b64 s[6:7], -1
	s_waitcnt lgkmcnt(0)
	v_cmp_le_i32_e32 vcc, s65, v0
	v_readfirstlane_b32 s64, v0
	s_cbranch_vccnz .LBB0_72
	v_ashrrev_i32_e32 v97, 6, v164
	s_cmpk_gt_i32 s64, 0x7f
	s_cbranch_scc0 .LBB0_197
	s_cmpk_gt_u32 s64, 0x17f
	s_cbranch_scc0 .LBB0_124
	s_cmpk_gt_u32 s64, 0x37f
	s_cbranch_scc0 .LBB0_115
	s_load_dwordx2 s[12:13], s[88:89], 0x80
	s_load_dwordx2 s[14:15], s[88:89], 0x68
	s_load_dwordx4 s[16:19], s[88:89], 0x10
	s_load_dwordx2 s[20:21], s[88:89], 0x98
	s_sub_u32 s6, s64, 0x380
	s_mov_b32 s27, 0
	s_waitcnt lgkmcnt(0)
	s_cmp_lt_u32 s6, 0x80
	s_cbranch_scc1 .Lcvm_wout0
	s_cmp_lt_u32 s6, 0x90
	s_cbranch_scc1 .Lcvm_glu0
	s_cmp_lt_u32 s6, 0x210
	s_cbranch_scc1 .Lcvm_win1
	s_cmp_lt_u32 s6, 0x290
	s_cbranch_scc1 .Lcvm_wout1
	s_cmp_lt_u32 s6, 0x2a0
	s_cbranch_scc1 .Lcvm_glu1
	s_sub_u32 s6, s6, 0x2a0
	s_lshl_b32 s28, s6, 18
	s_add_u32 s8, s18, s28
	s_addc_u32 s9, s19, 0
	s_add_u32 s8, s8, 0x100000
	s_addc_u32 s9, s9, 0
	s_lshl_b32 s28, s6, 17
	s_add_u32 s22, s20, s28
	s_addc_u32 s23, s21, 0
	s_add_u32 s22, s22, 0x10880000
	s_addc_u32 s23, s23, 0
	s_movk_i32 s24, 0x100
	s_movk_i32 s25, 0x100
	s_mov_b32 s26, 0
	s_mov_b32 s28, 0
	s_mov_b32 s29, 0
	s_branch .Lcvm_common

; __device__ __forceinline__ void phase_prep(const Params& p) {
;   __shared__ int s_pitem;
;   int* ctr = (int*)(p.ws + WS_CTR) + 8;
;   constexpr int N_SP = 128, N_CV = CV_A, N_RN = T / 8;
; #pragma unroll 1
;   for (;;) {
;     const int tid = opaque_tid();
;     __syncthreads();
;     if (tid == 0) s_pitem = atomicAdd(ctr, 1);
;     __syncthreads();
;     int it = s_pitem;
;     if (it >= N_SP + N_CV + N_RN) break;
.LBB0_250:
	s_and_b64 vcc, exec, s[6:7]
	s_movk_i32 s36, 0x4000
	s_mov_b32 s37, 0x8000
	s_movk_i32 s38, 0x3000
	s_movk_i32 s39, 0x1f8
	s_movk_i32 s92, 0x5000
	s_mov_b32 s1, 0x800000
	s_mov_b32 s57, 0xc000
	s_mov_b32 s58, 0x3fb8aa3b
	s_mov_b32 s80, 0xc2ce8ed0
	s_mov_b32 s81, 0x42b17218
	s_brev_b32 s82, 18
	s_mov_b32 s83, 0xfe5163ab
	s_mov_b32 s84, 0x3c439041
	s_mov_b32 s85, 0xdb629599
	s_cbranch_vccz .LBB0_299
	s_mov_b32 s98, 0
	s_add_u32 s12, s86, 0x43d10020
	s_addc_u32 s13, s87, 0
	s_add_u32 s14, s86, 0x10900000
	s_addc_u32 s15, s87, 0
	s_add_u32 s24, s86, 0x10800000
	s_addc_u32 s25, s87, 0
	s_add_u32 s26, s86, 0x3fd00000
	s_addc_u32 s27, s87, 0
	s_add_u32 s28, s86, 0x41d00000
	s_addc_u32 s29, s87, 0
	s_add_u32 s30, s86, 0x43d00000
	s_addc_u32 s31, s87, 0
	s_add_u32 s34, s86, 0x3f900000
	s_addc_u32 s35, s87, 0
	s_branch .LBB0_254

; __device__ __forceinline__ void rmsnorm_rows(const float* __restrict__ xin, const float* __restrict__ g, u16* outb, float* outf,
;                                              int row_begin, int row_end, int row_step, const int tidx) {
;     ...
;   for (int row = row_begin; row < row_end; row += row_step) {
;     const float* xr = xin + (size_t)row * DM;
;     f32x4 v[16];
;     float ss = 0.f;
; #pragma unroll
;     for (int i = 0; i < 16; ++i) {
;       v[i] = *reinterpret_cast<const f32x4*>(xr + i * 256 + lane * 4);
;     }
; __device__ __forceinline__ void phase_prep(const Params& p) {
;     ...
;   for (;;) {
;     const int tid = opaque_tid();
;     __syncthreads();
;     if (tid == 0) s_pitem = atomicAdd(ctr, 1);
;     __syncthreads();
;     int it = s_pitem;
;     if (it >= N_SP + N_CV + N_RN) break;
;     if (it < N_SP) {
;       ssm_prep_item(p, it);
;     } else if (it < N_SP + N_CV) {
;       it -= N_SP;
;       if (it < CV_IN) cv_in(p, 0, it, tid);
;       else cv_pool(p, 0, it - CV_IN, tid);
;     } else {
;       int row = (it - N_SP - N_CV) * 8 + (tid >> 6);
;       rmsnorm_rows(p.x, p.ln_g, (u16*)(p.ws + WS_H), nullptr, row, row + 1, 1, tid);
.LBB0_254:
	v_mov_b32_e32 v130, v210
	s_waitcnt vmcnt(0)
	v_cmp_eq_u32_e32 vcc, 0, v130
	s_barrier
	s_and_saveexec_b64 s[6:7], vcc
	s_cbranch_execz .LBB0_258
	s_cmp_lg_u32 s98, 0
	s_cbranch_scc1 .Lqp_have
	v_mov_b32_e32 v1, 1
	global_atomic_add v252, v163, v1, s[12:13] sc0
.Lqp_have:
	s_waitcnt vmcnt(0)
	v_mov_b32_e32 v0, v252
	ds_write_b32 v163, v0 offset:16
	v_readfirstlane_b32 s8, v0
	s_mov_b32 s98, 0
	s_nop 1
	s_sub_u32 s8, s8, 0x204
	s_cmp_lt_u32 s8, 0x400
	s_cbranch_scc0 .Lqp_done
	v_mov_b32_e32 v1, 1
	global_atomic_add v252, v163, v1, s[12:13] sc0
	s_mov_b32 s98, 1
.Lqp_done:
.LBB0_258:
	s_or_b64 exec, exec, s[6:7]
	s_waitcnt lgkmcnt(0)
	s_barrier
	ds_read_b32 v0, v163 offset:16
	s_movk_i32 s6, 0x603
	s_waitcnt lgkmcnt(0)
	v_cmp_lt_i32_e32 vcc, s6, v0
	v_readfirstlane_b32 s16, v0
	s_mov_b64 s[6:7], -1
	s_cbranch_vccnz .LBB0_253
	s_cmpk_gt_i32 s16, 0x7f
	s_cbranch_scc0 .LBB0_272
	s_cmpk_gt_u32 s16, 0x203
	s_cbranch_scc0 .LBB0_262
	v_ashrrev_i32_e32 v0, 6, v130
	v_lshl_add_u32 v0, s16, 3, v0
	v_add_u32_e32 v132, 0xffffefe0, v0
	v_lshlrev_b32_e32 v0, 2, v130
	v_and_b32_e32 v97, 0xfc, v0
	v_readlane_b32 s64, v254, 33
	v_lshlrev_b32_e32 v162, 2, v97
	v_readlane_b32 s66, v254, 35
	v_readlane_b32 s67, v254, 36
	s_nop 4
	global_load_dwordx4 v[102:105], v162, s[66:67]
	global_load_dwordx4 v[98:101], v162, s[66:67] offset:1024
	global_load_dwordx4 v[88:91], v162, s[66:67] offset:2048
	global_load_dwordx4 v[80:83], v162, s[66:67] offset:3072
	v_lshl_add_u64 v[0:1], s[66:67], 0, v[162:163]
	v_add_co_u32_e32 v2, vcc, 0x1000, v0
	v_readlane_b32 s65, v254, 34
	s_nop 0
	v_addc_co_u32_e32 v3, vcc, 0, v1, vcc
	global_load_dwordx4 v[76:79], v[2:3], off
	global_load_dwordx4 v[68:71], v[2:3], off offset:1024
	global_load_dwordx4 v[56:59], v[2:3], off offset:2048
	global_load_dwordx4 v[40:43], v[2:3], off offset:3072
	v_add_co_u32_e32 v2, vcc, s51, v0
	v_ashrrev_i32_e32 v133, 31, v132
	s_nop 0
	v_addc_co_u32_e32 v3, vcc, 0, v1, vcc
	v_add_co_u32_e32 v0, vcc, s38, v0
	v_lshl_add_u64 v[24:25], s[64:65], 0, v[162:163]
	v_lshlrev_b64 v[26:27], 14, v[132:133]
	v_addc_co_u32_e32 v1, vcc, 0, v1, vcc
	v_lshl_add_u64 v[24:25], v[24:25], 0, v[26:27]
	v_add_co_u32_e32 v26, vcc, s56, v24
	global_load_dwordx4 v[32:35], v[2:3], off offset:1024
	global_load_dwordx4 v[20:23], v[2:3], off offset:2048
	global_load_dwordx4 v[16:19], v[2:3], off offset:3072
	global_load_dwordx4 v[44:47], v[0:1], off offset:-4096
	global_load_dwordx4 v[12:15], v[0:1], off
	global_load_dwordx4 v[8:11], v[0:1], off offset:1024
	global_load_dwordx4 v[4:7], v[0:1], off offset:2048
	s_nop 0
	global_load_dwordx4 v[0:3], v[0:1], off offset:3072
	v_addc_co_u32_e32 v27, vcc, 0, v25, vcc
	v_add_co_u32_e32 v28, vcc, s51, v24
	global_load_dwordx4 v[126:129], v[24:25], off
	global_load_dwordx4 v[122:125], v[24:25], off offset:1024
	global_load_dwordx4 v[118:121], v[24:25], off offset:2048
	global_load_dwordx4 v[114:117], v[24:25], off offset:3072
	v_addc_co_u32_e32 v29, vcc, 0, v25, vcc
	global_load_dwordx4 v[106:109], v[26:27], off offset:1024
	global_load_dwordx4 v[92:95], v[26:27], off offset:2048
	global_load_dwordx4 v[110:113], v[28:29], off offset:-4096
	global_load_dwordx4 v[72:75], v[28:29], off
	global_load_dwordx4 v[64:67], v[28:29], off offset:1024
	global_load_dwordx4 v[60:63], v[28:29], off offset:2048
	global_load_dwordx4 v[52:55], v[28:29], off offset:3072
	v_add_co_u32_e32 v24, vcc, s38, v24
	v_and_b32_e32 v131, 64, v215
	s_nop 0
	v_addc_co_u32_e32 v25, vcc, 0, v25, vcc
	global_load_dwordx4 v[84:87], v[26:27], off offset:3072
	global_load_dwordx4 v[48:51], v[24:25], off
	global_load_dwordx4 v[36:39], v[24:25], off offset:1024
	global_load_dwordx4 v[28:31], v[24:25], off offset:2048
	s_nop 0
	global_load_dwordx4 v[24:27], v[24:25], off offset:3072
	v_add_u32_e32 v131, 64, v131
	v_xor_b32_e32 v134, 32, v215
	v_cmp_lt_i32_e32 vcc, v134, v131
	s_mov_b64 s[54:55], 0x10040100
	s_mov_b64 s[60:61], 0x2e940180
	v_cndmask_b32_e32 v134, v215, v134, vcc
	v_lshlrev_b32_e32 v140, 2, v134
	v_xor_b32_e32 v134, 16, v215
	v_cmp_lt_i32_e32 vcc, v134, v131
	s_mov_b64 s[52:53], 0x10000180
	s_mov_b64 s[46:47], 0x2e900180
	v_cndmask_b32_e32 v134, v215, v134, vcc
	v_lshlrev_b32_e32 v141, 2, v134
	v_xor_b32_e32 v134, 8, v215
	v_cmp_lt_i32_e32 vcc, v134, v131
	s_mov_b64 s[96:97], 0x2e940100
	s_movk_i32 s33, 0x44
	v_cndmask_b32_e32 v134, v215, v134, vcc
	v_lshlrev_b32_e32 v142, 2, v134
	v_xor_b32_e32 v134, 4, v215
	v_cmp_lt_i32_e32 vcc, v134, v131
	s_movk_i32 s0, 0x3c0
	v_lshlrev_b32_e32 v162, 1, v97
	v_cndmask_b32_e32 v134, v215, v134, vcc
	v_lshlrev_b32_e32 v143, 2, v134
	v_xor_b32_e32 v134, 2, v215
	v_cmp_lt_i32_e32 vcc, v134, v131
	v_readlane_b32 s68, v254, 37
	v_readlane_b32 s69, v254, 38
	v_cndmask_b32_e32 v134, v215, v134, vcc
	v_lshlrev_b32_e32 v144, 2, v134
	v_xor_b32_e32 v134, 1, v215
	v_cmp_lt_i32_e32 vcc, v134, v131
	v_readlane_b32 s70, v254, 39
	v_readlane_b32 s71, v254, 40
	v_cndmask_b32_e32 v131, v215, v134, vcc
	v_readlane_b32 s72, v254, 41
	v_readlane_b32 s73, v254, 42
	v_readlane_b32 s74, v254, 43
	v_readlane_b32 s75, v254, 44
	v_readlane_b32 s76, v254, 45
	v_readlane_b32 s77, v254, 46
	v_readlane_b32 s78, v254, 47
	v_readlane_b32 s79, v254, 48
	v_lshlrev_b32_e32 v131, 2, v131
	v_lshl_add_u64 v[134:135], s[14:15], 0, v[162:163]
	s_waitcnt vmcnt(3)
	v_mov_b32_e32 v138, v49
	s_waitcnt vmcnt(2)
; __device__ __forceinline__ void rmsnorm_rows(const float* __restrict__ xin, const float* __restrict__ g, u16* outb, float* outf,
;                                              int row_begin, int row_end, int row_step, const int tidx) {
;     ...
; #pragma unroll
;     for (int i = 0; i < 16; ++i) ss += v[i][0] * v[i][0] + v[i][1] * v[i][1] + v[i][2] * v[i][2] + v[i][3] * v[i][3];
;     ss = wave_sum(ss);
;     float rs = rsqrtf(ss * (1.f / DM) + 1e-6f);
	v_mov_b32_e32 v139, v37
	v_mov_b32_e32 v136, v48
	v_mov_b32_e32 v137, v36
	v_pk_mul_f32 v[138:139], v[138:139], v[138:139]
	v_mul_f32_e32 v97, v127, v127
	v_pk_fma_f32 v[136:137], v[136:137], v[136:137], v[138:139]
	v_mov_b32_e32 v138, v50
	v_mov_b32_e32 v139, v38
	v_pk_fma_f32 v[136:137], v[138:139], v[138:139], v[136:137]
	v_mov_b32_e32 v138, v51
	v_mov_b32_e32 v139, v39
	v_pk_fma_f32 v[136:137], v[138:139], v[138:139], v[136:137]
	v_mul_f32_e32 v138, v123, v123
	v_fmac_f32_e32 v97, v126, v126
	v_fmac_f32_e32 v138, v122, v122
	v_fmac_f32_e32 v97, v128, v128
	v_fmac_f32_e32 v138, v124, v124
	v_fmac_f32_e32 v97, v129, v129
	v_fmac_f32_e32 v138, v125, v125
	v_add_f32_e32 v97, v97, v138
	v_mul_f32_e32 v138, v119, v119
	v_fmac_f32_e32 v138, v118, v118
	v_fmac_f32_e32 v138, v120, v120
	v_fmac_f32_e32 v138, v121, v121
	v_add_f32_e32 v97, v97, v138
	v_mul_f32_e32 v138, v115, v115
	v_fmac_f32_e32 v138, v114, v114
	v_fmac_f32_e32 v138, v116, v116
	v_fmac_f32_e32 v138, v117, v117
	v_add_f32_e32 v97, v97, v138
	v_mul_f32_e32 v138, v111, v111
	v_fmac_f32_e32 v138, v110, v110
	v_fmac_f32_e32 v138, v112, v112
	v_fmac_f32_e32 v138, v113, v113
	v_add_f32_e32 v97, v97, v138
	v_mul_f32_e32 v138, v107, v107
	v_fmac_f32_e32 v138, v106, v106
	v_fmac_f32_e32 v138, v108, v108
	v_fmac_f32_e32 v138, v109, v109
	v_add_f32_e32 v97, v97, v138
	v_mul_f32_e32 v138, v93, v93
	v_fmac_f32_e32 v138, v92, v92
	v_fmac_f32_e32 v138, v94, v94
	v_fmac_f32_e32 v138, v95, v95
	v_add_f32_e32 v97, v97, v138
	v_mul_f32_e32 v138, v85, v85
	v_fmac_f32_e32 v138, v84, v84
	v_fmac_f32_e32 v138, v86, v86
	v_fmac_f32_e32 v138, v87, v87
	v_add_f32_e32 v97, v97, v138
	v_mul_f32_e32 v138, v73, v73
	v_fmac_f32_e32 v138, v72, v72
	v_fmac_f32_e32 v138, v74, v74
	v_fmac_f32_e32 v138, v75, v75
	v_add_f32_e32 v97, v97, v138
	v_mul_f32_e32 v138, v65, v65
	v_fmac_f32_e32 v138, v64, v64
	v_fmac_f32_e32 v138, v66, v66
	v_fmac_f32_e32 v138, v67, v67
	v_add_f32_e32 v97, v97, v138
	v_mul_f32_e32 v138, v61, v61
	v_fmac_f32_e32 v138, v60, v60
	v_fmac_f32_e32 v138, v62, v62
	v_fmac_f32_e32 v138, v63, v63
	v_add_f32_e32 v97, v97, v138
	v_mul_f32_e32 v138, v53, v53
	v_fmac_f32_e32 v138, v52, v52
	v_fmac_f32_e32 v138, v54, v54
	v_fmac_f32_e32 v138, v55, v55
	v_add_f32_e32 v97, v97, v138
	v_add_f32_e32 v97, v97, v136
	s_waitcnt vmcnt(1)
	v_mov_b32_e32 v138, v29
	s_waitcnt vmcnt(0)
	v_mov_b32_e32 v139, v25
	v_add_f32_e32 v97, v97, v137
	v_mov_b32_e32 v136, v28
	v_mov_b32_e32 v137, v24
	v_pk_mul_f32 v[138:139], v[138:139], v[138:139]
	s_mov_b64 s[6:7], 0
	v_pk_fma_f32 v[136:137], v[136:137], v[136:137], v[138:139]
	v_mov_b32_e32 v138, v30
	v_mov_b32_e32 v139, v26
	v_pk_fma_f32 v[136:137], v[138:139], v[138:139], v[136:137]
	v_mov_b32_e32 v138, v31
	v_mov_b32_e32 v139, v27
	v_pk_fma_f32 v[136:137], v[138:139], v[138:139], v[136:137]
	s_nop 0
	v_add_f32_e32 v97, v97, v136
	v_add_f32_e32 v97, v97, v137
	ds_bpermute_b32 v136, v140, v97
	s_waitcnt lgkmcnt(0)
	v_add_f32_e32 v97, v97, v136
	ds_bpermute_b32 v136, v141, v97
	s_waitcnt lgkmcnt(0)
	v_add_f32_e32 v97, v97, v136
	ds_bpermute_b32 v136, v142, v97
	s_waitcnt lgkmcnt(0)
	v_add_f32_e32 v97, v97, v136
	ds_bpermute_b32 v136, v143, v97
	s_waitcnt lgkmcnt(0)
	v_add_f32_e32 v97, v97, v136
	ds_bpermute_b32 v136, v144, v97
	s_waitcnt lgkmcnt(0)
	v_add_f32_e32 v97, v97, v136
	ds_bpermute_b32 v131, v131, v97
	s_waitcnt lgkmcnt(0)
; __device__ __forceinline__ void rmsnorm_rows(const float* __restrict__ xin, const float* __restrict__ g, u16* outb, float* outf,
;                                              int row_begin, int row_end, int row_step, const int tidx) {
;     ...
;     float rs = rsqrtf(ss * (1.f / DM) + 1e-6f);
; #pragma unroll
;     for (int i = 0; i < 16; ++i) {
;       f32x4 o = v[i] * rs * ggv[i];
;       if (outb) {
;         u32x2 pk;
;         pk.x = pack2(o[0], o[1]);
;         pk.y = pack2(o[2], o[3]);
;         *reinterpret_cast<u32x2*>(outb + (size_t)row * DM + i * 256 + lane * 4) = pk;
;       } else {
;         *reinterpret_cast<f32x4*>(outf + (size_t)row * DM + i * 256 + lane * 4) = o;
;       }
;     }
	v_add_f32_e32 v97, v97, v131
	v_fmamk_f32 v97, v97, 0x39800000, v211
	v_mul_f32_e32 v131, 0x4b800000, v97
	v_cmp_gt_f32_e32 vcc, s1, v97
	s_nop 1
	v_cndmask_b32_e32 v97, v97, v131, vcc
	v_rsq_f32_e32 v97, v97
	s_nop 0
	v_mul_f32_e32 v131, 0x45800000, v97
	v_cndmask_b32_e32 v136, v97, v131, vcc
	v_pk_mul_f32 v[106:107], v[106:107], v[136:137] op_sel_hi:[1,0]
	v_pk_mul_f32 v[108:109], v[108:109], v[136:137] op_sel_hi:[1,0]
	v_pk_mul_f32 v[68:69], v[68:69], v[106:107]
	v_lshlrev_b64 v[106:107], 13, v[132:133]
	v_pk_mul_f32 v[70:71], v[70:71], v[108:109]
	v_lshl_add_u64 v[106:107], v[134:135], 0, v[106:107]
	v_cvt_pk_bf16_f32 v68, v68, v69
	v_cvt_pk_bf16_f32 v69, v70, v71
	global_store_dwordx2 v[106:107], v[68:69], off offset:2560
	v_pk_mul_f32 v[68:69], v[92:93], v[136:137] op_sel_hi:[1,0]
	v_pk_mul_f32 v[70:71], v[94:95], v[136:137] op_sel_hi:[1,0]
	v_pk_mul_f32 v[56:57], v[56:57], v[68:69]
	v_pk_mul_f32 v[58:59], v[58:59], v[70:71]
	v_cvt_pk_bf16_f32 v56, v56, v57
	v_pk_mul_f32 v[126:127], v[126:127], v[136:137] op_sel_hi:[1,0]
	v_cvt_pk_bf16_f32 v57, v58, v59
	global_store_dwordx2 v[106:107], v[56:57], off offset:3072
	v_pk_mul_f32 v[56:57], v[84:85], v[136:137] op_sel_hi:[1,0]
	v_pk_mul_f32 v[58:59], v[86:87], v[136:137] op_sel_hi:[1,0]
	v_pk_mul_f32 v[40:41], v[40:41], v[56:57]
	v_pk_mul_f32 v[42:43], v[42:43], v[58:59]
	v_cvt_pk_bf16_f32 v40, v40, v41
	v_pk_mul_f32 v[122:123], v[122:123], v[136:137] op_sel_hi:[1,0]
	v_cvt_pk_bf16_f32 v41, v42, v43
	global_store_dwordx2 v[106:107], v[40:41], off offset:3584
	v_pk_mul_f32 v[40:41], v[72:73], v[136:137] op_sel_hi:[1,0]
	v_pk_mul_f32 v[42:43], v[74:75], v[136:137] op_sel_hi:[1,0]
	v_pk_mul_f32 v[40:41], v[44:45], v[40:41]
	v_pk_mul_f32 v[42:43], v[46:47], v[42:43]
	v_cvt_pk_bf16_f32 v40, v40, v41
	v_pk_mul_f32 v[44:45], v[66:67], v[136:137] op_sel_hi:[1,0]
	v_cvt_pk_bf16_f32 v41, v42, v43
	v_add_co_u32_e32 v42, vcc, s56, v106
	v_pk_mul_f32 v[34:35], v[34:35], v[44:45]
	s_nop 0
	v_addc_co_u32_e32 v43, vcc, 0, v107, vcc
	global_store_dwordx2 v[42:43], v[40:41], off
	v_pk_mul_f32 v[40:41], v[64:65], v[136:137] op_sel_hi:[1,0]
	v_pk_mul_f32 v[118:119], v[118:119], v[136:137] op_sel_hi:[1,0]
	v_pk_mul_f32 v[32:33], v[32:33], v[40:41]
	v_pk_mul_f32 v[114:115], v[114:115], v[136:137] op_sel_hi:[1,0]
	v_cvt_pk_bf16_f32 v32, v32, v33
	v_cvt_pk_bf16_f32 v33, v34, v35
	global_store_dwordx2 v[42:43], v[32:33], off offset:512
	v_pk_mul_f32 v[32:33], v[60:61], v[136:137] op_sel_hi:[1,0]
	v_pk_mul_f32 v[34:35], v[62:63], v[136:137] op_sel_hi:[1,0]
	v_pk_mul_f32 v[20:21], v[20:21], v[32:33]
	v_pk_mul_f32 v[22:23], v[22:23], v[34:35]
	v_cvt_pk_bf16_f32 v20, v20, v21
	v_pk_mul_f32 v[110:111], v[110:111], v[136:137] op_sel_hi:[1,0]
	v_cvt_pk_bf16_f32 v21, v22, v23
	global_store_dwordx2 v[42:43], v[20:21], off offset:1024
	v_pk_mul_f32 v[20:21], v[52:53], v[136:137] op_sel_hi:[1,0]
	v_pk_mul_f32 v[22:23], v[54:55], v[136:137] op_sel_hi:[1,0]
	v_pk_mul_f32 v[16:17], v[16:17], v[20:21]
	v_pk_mul_f32 v[18:19], v[18:19], v[22:23]
	v_cvt_pk_bf16_f32 v16, v16, v17
	v_pk_mul_f32 v[128:129], v[128:129], v[136:137] op_sel_hi:[1,0]
	v_cvt_pk_bf16_f32 v17, v18, v19
	global_store_dwordx2 v[42:43], v[16:17], off offset:1536
	v_pk_mul_f32 v[16:17], v[48:49], v[136:137] op_sel_hi:[1,0]
	v_pk_mul_f32 v[18:19], v[50:51], v[136:137] op_sel_hi:[1,0]
	v_pk_mul_f32 v[12:13], v[12:13], v[16:17]
	v_pk_mul_f32 v[14:15], v[14:15], v[18:19]
	v_cvt_pk_bf16_f32 v12, v12, v13
	v_pk_mul_f32 v[102:103], v[102:103], v[126:127]
	v_cvt_pk_bf16_f32 v13, v14, v15
	global_store_dwordx2 v[42:43], v[12:13], off offset:2048
	v_pk_mul_f32 v[12:13], v[36:37], v[136:137] op_sel_hi:[1,0]
	v_pk_mul_f32 v[14:15], v[38:39], v[136:137] op_sel_hi:[1,0]
	v_pk_mul_f32 v[8:9], v[8:9], v[12:13]
	v_pk_mul_f32 v[10:11], v[10:11], v[14:15]
	v_cvt_pk_bf16_f32 v8, v8, v9
	v_pk_mul_f32 v[124:125], v[124:125], v[136:137] op_sel_hi:[1,0]
	v_cvt_pk_bf16_f32 v9, v10, v11
	global_store_dwordx2 v[42:43], v[8:9], off offset:2560
	v_pk_mul_f32 v[8:9], v[28:29], v[136:137] op_sel_hi:[1,0]
	v_pk_mul_f32 v[10:11], v[30:31], v[136:137] op_sel_hi:[1,0]
	v_pk_mul_f32 v[4:5], v[4:5], v[8:9]
	v_pk_mul_f32 v[6:7], v[6:7], v[10:11]
	v_cvt_pk_bf16_f32 v4, v4, v5
	v_pk_mul_f32 v[98:99], v[98:99], v[122:123]
	v_cvt_pk_bf16_f32 v5, v6, v7
	global_store_dwordx2 v[42:43], v[4:5], off offset:3072
	v_pk_mul_f32 v[4:5], v[24:25], v[136:137] op_sel_hi:[1,0]
	v_pk_mul_f32 v[120:121], v[120:121], v[136:137] op_sel_hi:[1,0]
	v_pk_mul_f32 v[88:89], v[88:89], v[118:119]
	v_pk_mul_f32 v[116:117], v[116:117], v[136:137] op_sel_hi:[1,0]
	v_pk_mul_f32 v[80:81], v[80:81], v[114:115]
	v_pk_mul_f32 v[112:113], v[112:113], v[136:137] op_sel_hi:[1,0]
	v_pk_mul_f32 v[76:77], v[76:77], v[110:111]
	v_pk_mul_f32 v[6:7], v[26:27], v[136:137] op_sel_hi:[1,0]
	v_pk_mul_f32 v[0:1], v[0:1], v[4:5]
	v_pk_mul_f32 v[104:105], v[104:105], v[128:129]
	v_pk_mul_f32 v[100:101], v[100:101], v[124:125]
	v_pk_mul_f32 v[90:91], v[90:91], v[120:121]
	v_pk_mul_f32 v[82:83], v[82:83], v[116:117]
	v_pk_mul_f32 v[78:79], v[78:79], v[112:113]
	v_cvt_pk_bf16_f32 v102, v102, v103
	v_cvt_pk_bf16_f32 v103, v104, v105
	global_store_dwordx2 v[106:107], v[102:103], off
	v_cvt_pk_bf16_f32 v98, v98, v99
	v_cvt_pk_bf16_f32 v99, v100, v101
	global_store_dwordx2 v[106:107], v[98:99], off offset:512
	v_cvt_pk_bf16_f32 v88, v88, v89
	v_cvt_pk_bf16_f32 v89, v90, v91
	global_store_dwordx2 v[106:107], v[88:89], off offset:1024
	v_cvt_pk_bf16_f32 v80, v80, v81
	v_cvt_pk_bf16_f32 v81, v82, v83
	global_store_dwordx2 v[106:107], v[80:81], off offset:1536
	v_cvt_pk_bf16_f32 v76, v76, v77
	v_cvt_pk_bf16_f32 v77, v78, v79
	global_store_dwordx2 v[106:107], v[76:77], off offset:2048
	v_pk_mul_f32 v[2:3], v[2:3], v[6:7]
	v_cvt_pk_bf16_f32 v0, v0, v1
	s_nop 0
	v_cvt_pk_bf16_f32 v1, v2, v3
	global_store_dwordx2 v[42:43], v[0:1], off offset:3584

; __global__ void __launch_bounds__(NTHR, 2) mega(Params p_unused, int ph_lo, int ph_hi, int coop) {
;   int rep = 0;
	.amdhsa_kernel _Z4mega6Paramsiii
		.amdhsa_group_segment_fixed_size 32
		.amdhsa_private_segment_fixed_size 0
		.amdhsa_kernarg_size 432
		.amdhsa_user_sgpr_count 2
		.amdhsa_user_sgpr_dispatch_ptr 0
		.amdhsa_user_sgpr_queue_ptr 0
		.amdhsa_user_sgpr_kernarg_segment_ptr 1
		.amdhsa_user_sgpr_dispatch_id 0
		.amdhsa_user_sgpr_kernarg_preload_length 0
		.amdhsa_user_sgpr_kernarg_preload_offset 0
		.amdhsa_user_sgpr_private_segment_size 0
		.amdhsa_uses_dynamic_stack 0
		.amdhsa_enable_private_segment 0
		.amdhsa_system_sgpr_workgroup_id_x 1
		.amdhsa_system_sgpr_workgroup_id_y 0
		.amdhsa_system_sgpr_workgroup_id_z 0
		.amdhsa_system_sgpr_workgroup_info 0
		.amdhsa_system_vgpr_workitem_id 2
		.amdhsa_next_free_vgpr 256
		.amdhsa_next_free_sgpr 100
		.amdhsa_accum_offset 256
		.amdhsa_reserve_vcc 1
		.amdhsa_float_round_mode_32 0
		.amdhsa_float_round_mode_16_64 0
		.amdhsa_float_denorm_mode_32 3
		.amdhsa_float_denorm_mode_16_64 3
		.amdhsa_dx10_clamp 1
		.amdhsa_ieee_mode 1
		.amdhsa_fp16_overflow 0
		.amdhsa_tg_split 0
		.amdhsa_exception_fp_ieee_invalid_op 0
		.amdhsa_exception_fp_denorm_src 0
		.amdhsa_exception_fp_ieee_div_zero 0
		.amdhsa_exception_fp_ieee_overflow 0
		.amdhsa_exception_fp_ieee_underflow 0
		.amdhsa_exception_fp_ieee_inexact 0
		.amdhsa_exception_int_div_zero 0
	.end_amdhsa_kernel

; __global__ void __launch_bounds__(NTHR, 2) mega(Params p_unused, int ph_lo, int ph_hi, int coop) {
;   int rep = 0;
amdhsa.kernels:
  - .agpr_count:     0
    .args:
      - .offset:         0
        .size:           160
        .value_kind:     by_value
      - .offset:         160
        .size:           4
        .value_kind:     by_value
      - .offset:         164
        .size:           4
        .value_kind:     by_value
      - .offset:         168
        .size:           4
        .value_kind:     by_value
      - .offset:         176
        .size:           4
        .value_kind:     hidden_block_count_x
      - .offset:         180
        .size:           4
        .value_kind:     hidden_block_count_y
      - .offset:         184
        .size:           4
        .value_kind:     hidden_block_count_z
      - .offset:         188
        .size:           2
        .value_kind:     hidden_group_size_x
      - .offset:         190
        .size:           2
        .value_kind:     hidden_group_size_y
      - .offset:         192
        .size:           2
        .value_kind:     hidden_group_size_z
      - .offset:         194
        .size:           2
        .value_kind:     hidden_remainder_x
      - .offset:         196
        .size:           2
        .value_kind:     hidden_remainder_y
      - .offset:         198
        .size:           2
        .value_kind:     hidden_remainder_z
      - .offset:         216
        .size:           8
        .value_kind:     hidden_global_offset_x
      - .offset:         224
        .size:           8
        .value_kind:     hidden_global_offset_y
      - .offset:         232
        .size:           8
        .value_kind:     hidden_global_offset_z
      - .offset:         240
        .size:           2
        .value_kind:     hidden_grid_dims
      - .offset:         264
        .size:           8
        .value_kind:     hidden_multigrid_sync_arg
      - .offset:         296
        .size:           4
        .value_kind:     hidden_dynamic_lds_size
    .group_segment_fixed_size: 32
    .kernarg_segment_align: 8
    .kernarg_segment_size: 432
    .language:       OpenCL C
    .language_version:
      - 2
      - 0
    .max_flat_workgroup_size: 512
    .name:           _Z4mega6Paramsiii
    .private_segment_fixed_size: 0
    .sgpr_count:     106
    .sgpr_spill_count: 135
    .symbol:         _Z4mega6Paramsiii.kd
    .uniform_work_group_size: 1
    .uses_dynamic_stack: false
    .vgpr_count:     256
    .vgpr_spill_count: 0
    .wavefront_size: 64
